# v119 with the attention output stores written through at agent scope (sc1) instead of system scope (sc0 sc1)
# speedup vs baseline: 1.0124x; 1.0010x over previous
.Lat3_epi_b:
	v_mov_b32_e32 v15, v175
	s_nop 1
	v_permlane32_swap_b32_e32 v175, v15
	v_add_f32_e32 v175, v175, v15
	v_div_scale_f32 v2, s[16:17], v175, v175, 1.0
	v_div_scale_f32 v4, vcc, 1.0, v175, 1.0
	v_rcp_f32_e32 v3, v2
	s_nop 1
	v_fma_f32 v5, -v2, v3, 1.0
	v_fmac_f32_e32 v3, v5, v3
	v_mul_f32_e32 v5, v4, v3
	v_fma_f32 v213, -v2, v5, v4
	v_fmac_f32_e32 v5, v213, v3
	v_fma_f32 v2, -v2, v5, v4
	v_div_fmas_f32 v2, v2, v3, v5
	v_div_fixup_f32 v0, v2, v175, 1.0
	s_nop 4
	v_mul_f32_e32 v64, v64, v0
	v_mul_f32_e32 v65, v65, v0
	v_mul_f32_e32 v66, v66, v0
	v_mul_f32_e32 v67, v67, v0
	v_mul_f32_e32 v68, v68, v0
	v_mul_f32_e32 v69, v69, v0
	v_mul_f32_e32 v70, v70, v0
	v_mul_f32_e32 v71, v71, v0
	v_cvt_pk_bf16_f32 v6, v64, v65
	v_cvt_pk_bf16_f32 v7, v66, v67
	v_cvt_pk_bf16_f32 v8, v68, v69
	v_cvt_pk_bf16_f32 v9, v70, v71
	s_nop 1
	s_waitcnt vmcnt(23)
	v_mfma_f32_32x32x16_bf16 v[232:247], v[148:151], v[6:9], 0
	s_waitcnt vmcnt(22)
	v_mfma_f32_32x32x16_bf16 v[80:95], v[144:147], v[6:9], 0
	v_mul_f32_e32 v72, v72, v0
	v_mul_f32_e32 v73, v73, v0
	v_mul_f32_e32 v74, v74, v0
	v_mul_f32_e32 v75, v75, v0
	v_mul_f32_e32 v76, v76, v0
	v_mul_f32_e32 v77, v77, v0
	v_mul_f32_e32 v78, v78, v0
	v_mul_f32_e32 v79, v79, v0
	v_cvt_pk_bf16_f32 v10, v72, v73
	v_cvt_pk_bf16_f32 v11, v74, v75
	v_cvt_pk_bf16_f32 v12, v76, v77
	v_cvt_pk_bf16_f32 v13, v78, v79
	s_nop 1
	s_waitcnt vmcnt(21)
	v_mfma_f32_32x32x16_bf16 v[232:247], v[140:143], v[10:13], v[232:247]
	s_waitcnt vmcnt(20)
	v_mfma_f32_32x32x16_bf16 v[80:95], v[136:139], v[10:13], v[80:95]
	v_mul_f32_e32 v48, v48, v0
	v_mul_f32_e32 v49, v49, v0
	v_mul_f32_e32 v50, v50, v0
	v_mul_f32_e32 v51, v51, v0
	v_mul_f32_e32 v52, v52, v0
	v_mul_f32_e32 v53, v53, v0
	v_mul_f32_e32 v54, v54, v0
	v_mul_f32_e32 v55, v55, v0
	v_cvt_pk_bf16_f32 v6, v48, v49
	v_cvt_pk_bf16_f32 v7, v50, v51
	v_cvt_pk_bf16_f32 v8, v52, v53
	v_cvt_pk_bf16_f32 v9, v54, v55
	s_nop 1
	s_waitcnt vmcnt(19)
	v_mfma_f32_32x32x16_bf16 v[232:247], v[132:135], v[6:9], v[232:247]
	s_waitcnt vmcnt(18)
	v_mfma_f32_32x32x16_bf16 v[80:95], v[128:131], v[6:9], v[80:95]
	v_mul_f32_e32 v56, v56, v0
	v_mul_f32_e32 v57, v57, v0
	v_mul_f32_e32 v58, v58, v0
	v_mul_f32_e32 v59, v59, v0
	v_mul_f32_e32 v60, v60, v0
	v_mul_f32_e32 v61, v61, v0
	v_mul_f32_e32 v62, v62, v0
	v_mul_f32_e32 v63, v63, v0
	v_cvt_pk_bf16_f32 v10, v56, v57
	v_cvt_pk_bf16_f32 v11, v58, v59
	v_cvt_pk_bf16_f32 v12, v60, v61
	v_cvt_pk_bf16_f32 v13, v62, v63
	s_nop 1
	s_waitcnt vmcnt(17)
	v_mfma_f32_32x32x16_bf16 v[232:247], v[124:127], v[10:13], v[232:247]
	s_waitcnt vmcnt(16)
	v_mfma_f32_32x32x16_bf16 v[80:95], v[120:123], v[10:13], v[80:95]
	v_mul_f32_e32 v32, v32, v0
	v_mul_f32_e32 v33, v33, v0
	v_mul_f32_e32 v34, v34, v0
	v_mul_f32_e32 v35, v35, v0
	v_mul_f32_e32 v36, v36, v0
	v_mul_f32_e32 v37, v37, v0
	v_mul_f32_e32 v38, v38, v0
	v_mul_f32_e32 v39, v39, v0
	v_cvt_pk_bf16_f32 v6, v32, v33
	v_cvt_pk_bf16_f32 v7, v34, v35
	v_cvt_pk_bf16_f32 v8, v36, v37
	v_cvt_pk_bf16_f32 v9, v38, v39
	s_nop 1
	s_waitcnt vmcnt(15)
	v_mfma_f32_32x32x16_bf16 v[232:247], v[116:119], v[6:9], v[232:247]
	s_waitcnt vmcnt(14)
	v_mfma_f32_32x32x16_bf16 v[80:95], v[112:115], v[6:9], v[80:95]
	v_mul_f32_e32 v40, v40, v0
	v_mul_f32_e32 v41, v41, v0
	v_mul_f32_e32 v42, v42, v0
	v_mul_f32_e32 v43, v43, v0
	v_mul_f32_e32 v44, v44, v0
	v_mul_f32_e32 v45, v45, v0
	v_mul_f32_e32 v46, v46, v0
	v_mul_f32_e32 v47, v47, v0
	v_cvt_pk_bf16_f32 v10, v40, v41
	v_cvt_pk_bf16_f32 v11, v42, v43
	v_cvt_pk_bf16_f32 v12, v44, v45
	v_cvt_pk_bf16_f32 v13, v46, v47
	s_nop 1
	s_waitcnt vmcnt(13)
	v_mfma_f32_32x32x16_bf16 v[232:247], v[220:223], v[10:13], v[232:247]
	s_waitcnt vmcnt(12)
	v_mfma_f32_32x32x16_bf16 v[80:95], v[224:227], v[10:13], v[80:95]
	v_mul_f32_e32 v16, v16, v0
	v_mul_f32_e32 v17, v17, v0
	v_mul_f32_e32 v18, v18, v0
	v_mul_f32_e32 v19, v19, v0
	v_mul_f32_e32 v20, v20, v0
	v_mul_f32_e32 v21, v21, v0
	v_mul_f32_e32 v22, v22, v0
	v_mul_f32_e32 v23, v23, v0
	v_cvt_pk_bf16_f32 v6, v16, v17
	v_cvt_pk_bf16_f32 v7, v18, v19
	v_cvt_pk_bf16_f32 v8, v20, v21
	v_cvt_pk_bf16_f32 v9, v22, v23
	s_nop 1
	s_waitcnt vmcnt(11)
	v_mfma_f32_32x32x16_bf16 v[232:247], v[228:231], v[6:9], v[232:247]
	s_waitcnt vmcnt(10)
	v_mfma_f32_32x32x16_bf16 v[80:95], v[96:99], v[6:9], v[80:95]
	v_mul_f32_e32 v24, v24, v0
	v_mul_f32_e32 v25, v25, v0
	v_mul_f32_e32 v26, v26, v0
	v_mul_f32_e32 v27, v27, v0
	v_mul_f32_e32 v28, v28, v0
	v_mul_f32_e32 v29, v29, v0
	v_mul_f32_e32 v30, v30, v0
	v_mul_f32_e32 v31, v31, v0
	v_cvt_pk_bf16_f32 v10, v24, v25
	v_cvt_pk_bf16_f32 v11, v26, v27
	v_cvt_pk_bf16_f32 v12, v28, v29
	v_cvt_pk_bf16_f32 v13, v30, v31
	s_nop 1
	s_waitcnt vmcnt(9)
	v_mfma_f32_32x32x16_bf16 v[232:247], v[100:103], v[10:13], v[232:247]
	s_waitcnt vmcnt(8)
	v_mfma_f32_32x32x16_bf16 v[80:95], v[104:107], v[10:13], v[80:95]
	v_cmp_gt_u32_e32 vcc, s76, v167
	s_and_saveexec_b64 s[6:7], vcc
	s_cbranch_execz .LBB0_470
	s_nop 10
	s_waitcnt vmcnt(7)
	v_lshlrev_b32_e32 v2, 16, v190
	v_and_b32_e32 v3, 0xffff0000, v190
	v_lshlrev_b32_e32 v4, 16, v191
	v_and_b32_e32 v5, 0xffff0000, v191
	v_mul_f32_e32 v232, v232, v2
	v_mul_f32_e32 v233, v233, v3
	v_mul_f32_e32 v234, v234, v4
	v_mul_f32_e32 v235, v235, v5
	v_cvt_pk_bf16_f32 v190, v232, v233
	v_cvt_pk_bf16_f32 v191, v234, v235
	s_waitcnt vmcnt(6)
	v_lshlrev_b32_e32 v2, 16, v192
	v_and_b32_e32 v3, 0xffff0000, v192
	v_lshlrev_b32_e32 v4, 16, v193
	v_and_b32_e32 v5, 0xffff0000, v193
	v_mul_f32_e32 v236, v236, v2
	v_mul_f32_e32 v237, v237, v3
	v_mul_f32_e32 v238, v238, v4
	v_mul_f32_e32 v239, v239, v5
	v_cvt_pk_bf16_f32 v192, v236, v237
	v_cvt_pk_bf16_f32 v193, v238, v239
	s_waitcnt vmcnt(5)
	v_lshlrev_b32_e32 v2, 16, v194
	v_and_b32_e32 v3, 0xffff0000, v194
	v_lshlrev_b32_e32 v4, 16, v195
	v_and_b32_e32 v5, 0xffff0000, v195
	v_mul_f32_e32 v240, v240, v2
	v_mul_f32_e32 v241, v241, v3
	v_mul_f32_e32 v242, v242, v4
	v_mul_f32_e32 v243, v243, v5
	v_cvt_pk_bf16_f32 v194, v240, v241
	v_cvt_pk_bf16_f32 v195, v242, v243
	s_waitcnt vmcnt(4)
	v_lshlrev_b32_e32 v2, 16, v198
	v_and_b32_e32 v3, 0xffff0000, v198
	v_lshlrev_b32_e32 v4, 16, v199
	v_and_b32_e32 v5, 0xffff0000, v199
	v_mul_f32_e32 v244, v244, v2
	v_mul_f32_e32 v245, v245, v3
	v_mul_f32_e32 v246, v246, v4
	v_mul_f32_e32 v247, v247, v5
	v_cvt_pk_bf16_f32 v198, v244, v245
	v_cvt_pk_bf16_f32 v199, v246, v247
	s_waitcnt vmcnt(3)
	v_lshlrev_b32_e32 v2, 16, v200
	v_and_b32_e32 v3, 0xffff0000, v200
	v_lshlrev_b32_e32 v4, 16, v201
	v_and_b32_e32 v5, 0xffff0000, v201
	v_mul_f32_e32 v80, v80, v2
	v_mul_f32_e32 v81, v81, v3
	v_mul_f32_e32 v82, v82, v4
	v_mul_f32_e32 v83, v83, v5
	v_cvt_pk_bf16_f32 v200, v80, v81
	v_cvt_pk_bf16_f32 v201, v82, v83
	s_waitcnt vmcnt(2)
	v_lshlrev_b32_e32 v2, 16, v202
	v_and_b32_e32 v3, 0xffff0000, v202
	v_lshlrev_b32_e32 v4, 16, v203
	v_and_b32_e32 v5, 0xffff0000, v203
	v_mul_f32_e32 v84, v84, v2
	v_mul_f32_e32 v85, v85, v3
	v_mul_f32_e32 v86, v86, v4
	v_mul_f32_e32 v87, v87, v5
	v_cvt_pk_bf16_f32 v202, v84, v85
	v_cvt_pk_bf16_f32 v203, v86, v87
	s_waitcnt vmcnt(1)
	v_lshlrev_b32_e32 v2, 16, v216
	v_and_b32_e32 v3, 0xffff0000, v216
	v_lshlrev_b32_e32 v4, 16, v217
	v_and_b32_e32 v5, 0xffff0000, v217
	v_mul_f32_e32 v88, v88, v2
	v_mul_f32_e32 v89, v89, v3
	v_mul_f32_e32 v90, v90, v4
	v_mul_f32_e32 v91, v91, v5
	v_cvt_pk_bf16_f32 v216, v88, v89
	v_cvt_pk_bf16_f32 v217, v90, v91
	s_waitcnt vmcnt(0)
	v_lshlrev_b32_e32 v2, 16, v248
	v_and_b32_e32 v3, 0xffff0000, v248
	v_lshlrev_b32_e32 v4, 16, v249
	v_and_b32_e32 v5, 0xffff0000, v249
	v_mul_f32_e32 v92, v92, v2
	v_mul_f32_e32 v93, v93, v3
	v_mul_f32_e32 v94, v94, v4
	v_mul_f32_e32 v95, v95, v5
	v_cvt_pk_bf16_f32 v248, v92, v93
	v_cvt_pk_bf16_f32 v249, v94, v95
	global_store_dwordx2 v212, v[190:191], s[52:53] offset:0 sc1
	global_store_dwordx2 v212, v[192:193], s[52:53] offset:16 sc1
	global_store_dwordx2 v212, v[194:195], s[52:53] offset:32 sc1
	global_store_dwordx2 v212, v[198:199], s[52:53] offset:48 sc1
	global_store_dwordx2 v212, v[200:201], s[52:53] offset:64 sc1
	global_store_dwordx2 v212, v[202:203], s[52:53] offset:80 sc1
	global_store_dwordx2 v212, v[216:217], s[52:53] offset:96 sc1
	global_store_dwordx2 v212, v[248:249], s[52:53] offset:112 sc1
	s_mov_b32 s96, s97
	s_branch .LBB0_470
.Lat3_epi_a:
	v_mov_b32_e32 v15, v175
	s_nop 1
	v_permlane32_swap_b32_e32 v175, v15
	v_add_f32_e32 v175, v175, v15
	v_div_scale_f32 v2, s[16:17], v175, v175, 1.0
	v_div_scale_f32 v4, vcc, 1.0, v175, 1.0
	v_rcp_f32_e32 v3, v2
	s_nop 1
	v_fma_f32 v5, -v2, v3, 1.0
	v_fmac_f32_e32 v3, v5, v3
	v_mul_f32_e32 v5, v4, v3
	v_fma_f32 v213, -v2, v5, v4
	v_fmac_f32_e32 v5, v213, v3
	v_fma_f32 v2, -v2, v5, v4
	v_div_fmas_f32 v2, v2, v3, v5
	v_div_fixup_f32 v0, v2, v175, 1.0
	s_nop 4
	v_mul_f32_e32 v64, v64, v0
	v_mul_f32_e32 v65, v65, v0
	v_mul_f32_e32 v66, v66, v0
	v_mul_f32_e32 v67, v67, v0
	v_mul_f32_e32 v68, v68, v0
	v_mul_f32_e32 v69, v69, v0
	v_mul_f32_e32 v70, v70, v0
	v_mul_f32_e32 v71, v71, v0
	v_cvt_pk_bf16_f32 v6, v64, v65
	v_cvt_pk_bf16_f32 v7, v66, v67
	v_cvt_pk_bf16_f32 v8, v68, v69
	v_cvt_pk_bf16_f32 v9, v70, v71
	s_nop 1
	s_waitcnt vmcnt(23)
	v_mfma_f32_32x32x16_bf16 v[232:247], v[148:151], v[6:9], 0
	s_waitcnt vmcnt(22)
	v_mfma_f32_32x32x16_bf16 v[96:111], v[144:147], v[6:9], 0
	v_mul_f32_e32 v72, v72, v0
	v_mul_f32_e32 v73, v73, v0
	v_mul_f32_e32 v74, v74, v0
	v_mul_f32_e32 v75, v75, v0
	v_mul_f32_e32 v76, v76, v0
	v_mul_f32_e32 v77, v77, v0
	v_mul_f32_e32 v78, v78, v0
	v_mul_f32_e32 v79, v79, v0
	v_cvt_pk_bf16_f32 v10, v72, v73
	v_cvt_pk_bf16_f32 v11, v74, v75
	v_cvt_pk_bf16_f32 v12, v76, v77
	v_cvt_pk_bf16_f32 v13, v78, v79
	s_nop 1
	s_waitcnt vmcnt(21)
	v_mfma_f32_32x32x16_bf16 v[232:247], v[140:143], v[10:13], v[232:247]
	s_waitcnt vmcnt(20)
	v_mfma_f32_32x32x16_bf16 v[96:111], v[136:139], v[10:13], v[96:111]
	v_mul_f32_e32 v48, v48, v0
	v_mul_f32_e32 v49, v49, v0
	v_mul_f32_e32 v50, v50, v0
	v_mul_f32_e32 v51, v51, v0
	v_mul_f32_e32 v52, v52, v0
	v_mul_f32_e32 v53, v53, v0
	v_mul_f32_e32 v54, v54, v0
	v_mul_f32_e32 v55, v55, v0
	v_cvt_pk_bf16_f32 v6, v48, v49
	v_cvt_pk_bf16_f32 v7, v50, v51
	v_cvt_pk_bf16_f32 v8, v52, v53
	v_cvt_pk_bf16_f32 v9, v54, v55
	s_nop 1
	s_waitcnt vmcnt(19)
	v_mfma_f32_32x32x16_bf16 v[232:247], v[132:135], v[6:9], v[232:247]
	s_waitcnt vmcnt(18)
	v_mfma_f32_32x32x16_bf16 v[96:111], v[128:131], v[6:9], v[96:111]
	v_mul_f32_e32 v56, v56, v0
	v_mul_f32_e32 v57, v57, v0
	v_mul_f32_e32 v58, v58, v0
	v_mul_f32_e32 v59, v59, v0
	v_mul_f32_e32 v60, v60, v0
	v_mul_f32_e32 v61, v61, v0
	v_mul_f32_e32 v62, v62, v0
	v_mul_f32_e32 v63, v63, v0
	v_cvt_pk_bf16_f32 v10, v56, v57
	v_cvt_pk_bf16_f32 v11, v58, v59
	v_cvt_pk_bf16_f32 v12, v60, v61
	v_cvt_pk_bf16_f32 v13, v62, v63
	s_nop 1
	s_waitcnt vmcnt(17)
	v_mfma_f32_32x32x16_bf16 v[232:247], v[124:127], v[10:13], v[232:247]
	s_waitcnt vmcnt(16)
	v_mfma_f32_32x32x16_bf16 v[96:111], v[120:123], v[10:13], v[96:111]
	v_mul_f32_e32 v32, v32, v0
	v_mul_f32_e32 v33, v33, v0
	v_mul_f32_e32 v34, v34, v0
	v_mul_f32_e32 v35, v35, v0
	v_mul_f32_e32 v36, v36, v0
	v_mul_f32_e32 v37, v37, v0
	v_mul_f32_e32 v38, v38, v0
	v_mul_f32_e32 v39, v39, v0
	v_cvt_pk_bf16_f32 v6, v32, v33
	v_cvt_pk_bf16_f32 v7, v34, v35
	v_cvt_pk_bf16_f32 v8, v36, v37
	v_cvt_pk_bf16_f32 v9, v38, v39
	s_nop 1
	s_waitcnt vmcnt(15)
	v_mfma_f32_32x32x16_bf16 v[232:247], v[116:119], v[6:9], v[232:247]
	s_waitcnt vmcnt(14)
	v_mfma_f32_32x32x16_bf16 v[96:111], v[112:115], v[6:9], v[96:111]
	v_mul_f32_e32 v40, v40, v0
	v_mul_f32_e32 v41, v41, v0
	v_mul_f32_e32 v42, v42, v0
	v_mul_f32_e32 v43, v43, v0
	v_mul_f32_e32 v44, v44, v0
	v_mul_f32_e32 v45, v45, v0
	v_mul_f32_e32 v46, v46, v0
	v_mul_f32_e32 v47, v47, v0
	v_cvt_pk_bf16_f32 v10, v40, v41
	v_cvt_pk_bf16_f32 v11, v42, v43
	v_cvt_pk_bf16_f32 v12, v44, v45
	v_cvt_pk_bf16_f32 v13, v46, v47
	s_nop 1
	s_waitcnt vmcnt(13)
	v_mfma_f32_32x32x16_bf16 v[232:247], v[220:223], v[10:13], v[232:247]
	s_waitcnt vmcnt(12)
	v_mfma_f32_32x32x16_bf16 v[96:111], v[224:227], v[10:13], v[96:111]
	v_mul_f32_e32 v16, v16, v0
	v_mul_f32_e32 v17, v17, v0
	v_mul_f32_e32 v18, v18, v0
	v_mul_f32_e32 v19, v19, v0
	v_mul_f32_e32 v20, v20, v0
	v_mul_f32_e32 v21, v21, v0
	v_mul_f32_e32 v22, v22, v0
	v_mul_f32_e32 v23, v23, v0
	v_cvt_pk_bf16_f32 v6, v16, v17
	v_cvt_pk_bf16_f32 v7, v18, v19
	v_cvt_pk_bf16_f32 v8, v20, v21
	v_cvt_pk_bf16_f32 v9, v22, v23
	s_nop 1
	s_waitcnt vmcnt(11)
	v_mfma_f32_32x32x16_bf16 v[232:247], v[228:231], v[6:9], v[232:247]
	s_waitcnt vmcnt(10)
	v_mfma_f32_32x32x16_bf16 v[96:111], v[80:83], v[6:9], v[96:111]
	v_mul_f32_e32 v24, v24, v0
	v_mul_f32_e32 v25, v25, v0
	v_mul_f32_e32 v26, v26, v0
	v_mul_f32_e32 v27, v27, v0
	v_mul_f32_e32 v28, v28, v0
	v_mul_f32_e32 v29, v29, v0
	v_mul_f32_e32 v30, v30, v0
	v_mul_f32_e32 v31, v31, v0
	v_cvt_pk_bf16_f32 v10, v24, v25
	v_cvt_pk_bf16_f32 v11, v26, v27
	v_cvt_pk_bf16_f32 v12, v28, v29
	v_cvt_pk_bf16_f32 v13, v30, v31
	s_nop 1
	s_waitcnt vmcnt(9)
	v_mfma_f32_32x32x16_bf16 v[232:247], v[84:87], v[10:13], v[232:247]
	s_waitcnt vmcnt(8)
	v_mfma_f32_32x32x16_bf16 v[96:111], v[88:91], v[10:13], v[96:111]
	v_cmp_gt_u32_e32 vcc, s76, v167
	s_and_saveexec_b64 s[6:7], vcc
	s_cbranch_execz .LBB0_470
	s_nop 10
	s_waitcnt vmcnt(7)
	v_lshlrev_b32_e32 v2, 16, v190
	v_and_b32_e32 v3, 0xffff0000, v190
	v_lshlrev_b32_e32 v4, 16, v191
	v_and_b32_e32 v5, 0xffff0000, v191
	v_mul_f32_e32 v232, v232, v2
	v_mul_f32_e32 v233, v233, v3
	v_mul_f32_e32 v234, v234, v4
	v_mul_f32_e32 v235, v235, v5
	v_cvt_pk_bf16_f32 v190, v232, v233
	v_cvt_pk_bf16_f32 v191, v234, v235
	s_waitcnt vmcnt(6)
	v_lshlrev_b32_e32 v2, 16, v192
	v_and_b32_e32 v3, 0xffff0000, v192
	v_lshlrev_b32_e32 v4, 16, v193
	v_and_b32_e32 v5, 0xffff0000, v193
	v_mul_f32_e32 v236, v236, v2
	v_mul_f32_e32 v237, v237, v3
	v_mul_f32_e32 v238, v238, v4
	v_mul_f32_e32 v239, v239, v5
	v_cvt_pk_bf16_f32 v192, v236, v237
	v_cvt_pk_bf16_f32 v193, v238, v239
	s_waitcnt vmcnt(5)
	v_lshlrev_b32_e32 v2, 16, v194
	v_and_b32_e32 v3, 0xffff0000, v194
	v_lshlrev_b32_e32 v4, 16, v195
	v_and_b32_e32 v5, 0xffff0000, v195
	v_mul_f32_e32 v240, v240, v2
	v_mul_f32_e32 v241, v241, v3
	v_mul_f32_e32 v242, v242, v4
	v_mul_f32_e32 v243, v243, v5
	v_cvt_pk_bf16_f32 v194, v240, v241
	v_cvt_pk_bf16_f32 v195, v242, v243
	s_waitcnt vmcnt(4)
	v_lshlrev_b32_e32 v2, 16, v198
	v_and_b32_e32 v3, 0xffff0000, v198
	v_lshlrev_b32_e32 v4, 16, v199
	v_and_b32_e32 v5, 0xffff0000, v199
	v_mul_f32_e32 v244, v244, v2
	v_mul_f32_e32 v245, v245, v3
	v_mul_f32_e32 v246, v246, v4
	v_mul_f32_e32 v247, v247, v5
	v_cvt_pk_bf16_f32 v198, v244, v245
	v_cvt_pk_bf16_f32 v199, v246, v247
	s_waitcnt vmcnt(3)
	v_lshlrev_b32_e32 v2, 16, v200
	v_and_b32_e32 v3, 0xffff0000, v200
	v_lshlrev_b32_e32 v4, 16, v201
	v_and_b32_e32 v5, 0xffff0000, v201
	v_mul_f32_e32 v96, v96, v2
	v_mul_f32_e32 v97, v97, v3
	v_mul_f32_e32 v98, v98, v4
	v_mul_f32_e32 v99, v99, v5
	v_cvt_pk_bf16_f32 v200, v96, v97
	v_cvt_pk_bf16_f32 v201, v98, v99
	s_waitcnt vmcnt(2)
	v_lshlrev_b32_e32 v2, 16, v202
	v_and_b32_e32 v3, 0xffff0000, v202
	v_lshlrev_b32_e32 v4, 16, v203
	v_and_b32_e32 v5, 0xffff0000, v203
	v_mul_f32_e32 v100, v100, v2
	v_mul_f32_e32 v101, v101, v3
	v_mul_f32_e32 v102, v102, v4
	v_mul_f32_e32 v103, v103, v5
	v_cvt_pk_bf16_f32 v202, v100, v101
	v_cvt_pk_bf16_f32 v203, v102, v103
	s_waitcnt vmcnt(1)
	v_lshlrev_b32_e32 v2, 16, v216
	v_and_b32_e32 v3, 0xffff0000, v216
	v_lshlrev_b32_e32 v4, 16, v217
	v_and_b32_e32 v5, 0xffff0000, v217
	v_mul_f32_e32 v104, v104, v2
	v_mul_f32_e32 v105, v105, v3
	v_mul_f32_e32 v106, v106, v4
	v_mul_f32_e32 v107, v107, v5
	v_cvt_pk_bf16_f32 v216, v104, v105
	v_cvt_pk_bf16_f32 v217, v106, v107
	s_waitcnt vmcnt(0)
	v_lshlrev_b32_e32 v2, 16, v248
	v_and_b32_e32 v3, 0xffff0000, v248
	v_lshlrev_b32_e32 v4, 16, v249
	v_and_b32_e32 v5, 0xffff0000, v249
	v_mul_f32_e32 v108, v108, v2
	v_mul_f32_e32 v109, v109, v3
	v_mul_f32_e32 v110, v110, v4
	v_mul_f32_e32 v111, v111, v5
	v_cvt_pk_bf16_f32 v248, v108, v109
	v_cvt_pk_bf16_f32 v249, v110, v111
	global_store_dwordx2 v212, v[190:191], s[52:53] offset:0 sc1
	global_store_dwordx2 v212, v[192:193], s[52:53] offset:16 sc1
	global_store_dwordx2 v212, v[194:195], s[52:53] offset:32 sc1
	global_store_dwordx2 v212, v[198:199], s[52:53] offset:48 sc1
	global_store_dwordx2 v212, v[200:201], s[52:53] offset:64 sc1
	global_store_dwordx2 v212, v[202:203], s[52:53] offset:80 sc1
	global_store_dwordx2 v212, v[216:217], s[52:53] offset:96 sc1
	global_store_dwordx2 v212, v[248:249], s[52:53] offset:112 sc1
	s_or_b64 exec, exec, s[6:7]
	s_mov_b64 s[6:7], 0
	s_waitcnt vmcnt(0)
	s_barrier
	s_and_saveexec_b64 s[18:19], s[80:81]
	s_cbranch_execz .Lat3_smpdone
	v_mov_b32_e32 v2, 0x3900
	v_mov_b32_e32 v3, 1
	global_atomic_add v2, v3, s[78:79]
